# bar_nowb + na_waits + P1 rotation 2
# baseline (speedup 1.0000x reference)
.LBB0_103:
	s_cmp_lt_i32 s82, 2
	s_cselect_b64 s[4:5], -1, 0
	s_add_u32 s6, s80, 0x1100000
	v_writelane_b32 v255, s84, 25
	s_addc_u32 s7, s81, 0
	v_writelane_b32 v255, s6, 26
	s_nop 1
	v_writelane_b32 v255, s7, 27
	s_add_u32 s6, s80, 0x1300000
	s_addc_u32 s7, s81, 0
	v_writelane_b32 v255, s6, 28
	s_nop 1
	v_writelane_b32 v255, s7, 29
	s_add_u32 s6, s80, 0x1b00000
	s_addc_u32 s7, s81, 0
	s_add_u32 s69, s80, 0x2600000
	v_writelane_b32 v255, s6, 30
	s_addc_u32 s70, s81, 0
	s_nop 0
	v_writelane_b32 v255, s7, 31
	s_add_u32 s6, s80, 0x2c00000
	s_addc_u32 s7, s81, 0
	s_add_u32 s60, s80, 0x8c00000
	s_addc_u32 s61, s81, 0
	s_add_u32 s96, s80, 0xdc00000
	s_addc_u32 s91, s81, 0
	s_add_u32 s62, s80, 0x7c00000
	v_writelane_b32 v255, s6, 32
	s_addc_u32 s63, s81, 0
	s_and_b64 s[28:29], s[4:5], s[0:1]
	v_writelane_b32 v255, s7, 33
	s_andn2_b64 vcc, exec, s[28:29]
	s_cbranch_vccnz .LBB0_220
	s_cmpk_lt_i32 s2, 0x590
	s_cselect_b64 s[4:5], -1, 0
	s_cmpk_gt_i32 s2, 0x58f
	v_readfirstlane_b32 s6, v216
	s_cbranch_scc1 .LBB0_107
	s_cmpk_gt_i32 s2, 0x57f
	s_cbranch_scc1 .LBB0_108
	s_ashr_i32 s0, s2, 31
	s_lshr_b32 s0, s0, 29
	s_add_i32 s0, s2, s0
	s_ashr_i32 s1, s0, 3
	s_and_b32 s0, s0, -8
	s_sub_i32 s0, s2, s0
	s_cmp_lt_i32 s0, 0
	s_movk_i32 s7, 0xb1
	s_cselect_b32 s7, s7, 0xb0
	s_mul_i32 s0, s0, s7
	s_add_i32 s0, s0, s1
	s_mul_hi_i32 s1, s0, 0x2e8ba2e9
	s_lshr_b32 s7, s1, 31
	s_ashr_i32 s1, s1, 5
	s_add_i32 s1, s1, s7
	s_lshl_b32 s7, s1, 3
	s_mulk_i32 s1, 0xb0
	s_sub_i32 s0, s0, s1
	s_sext_i32_i16 s1, s0
	s_bfe_u32 s1, s1, 0x3001c
	s_add_i32 s1, s0, s1
	s_bfe_u32 s8, s1, 0xd0003
	s_and_b32 s1, s1, 0xfff8
	s_sub_i32 s0, s0, s1
	s_sext_i32_i16 s0, s0
	s_add_i32 s8, s8, 2
	s_add_i32 s38, s7, s0
	s_bfe_i32 s0, s8, 0x80000
	s_mul_i32 s0, s0, 0xffbb
	s_bfe_u32 s0, s0, 0x80008
	s_add_i32 s0, s0, s8
	s_bfe_i32 s1, s0, 0x80000
	s_and_b32 s1, 0xffff, s1
	s_lshr_b32 s1, s1, 4
	s_bfe_u32 s0, s0, 0x10007
	s_add_i32 s0, s1, s0
	s_mul_i32 s0, s0, 22
	s_sub_i32 s0, s8, s0
	s_mov_b32 s59, 0
	s_sext_i32_i8 s90, s0
	s_mov_b64 s[0:1], -1
	s_andn2_b64 vcc, exec, s[4:5]
	v_lshlrev_b32_e32 v16, 2, v216
	s_cbranch_vccz .LBB0_109
	s_branch .LBB0_178

.LBB0_117:
	s_andn2_b64 vcc, exec, s[12:13]
	s_mov_b32 s69, 1
	s_cbranch_vccnz .LBB0_119
	s_ashr_i32 s5, s4, 31
	s_lshr_b32 s5, s5, 29
	s_add_i32 s5, s4, s5
	s_ashr_i32 s12, s5, 3
	s_and_b32 s5, s5, -8
	s_sub_i32 s4, s4, s5
	s_cmp_lt_i32 s4, 0
	s_movk_i32 s5, 0xb1
	s_cselect_b32 s5, s5, 0xb0
	s_mul_i32 s4, s4, s5
	s_add_i32 s4, s4, s12
	s_mul_hi_i32 s5, s4, 0x2e8ba2e9
	s_lshr_b32 s12, s5, 31
	s_ashr_i32 s5, s5, 5
	s_add_i32 s5, s5, s12
	s_lshl_b32 s12, s5, 3
	s_sub_i32 s13, 64, s12
	s_min_i32 s13, s13, 8
	s_abs_i32 s14, s13
	v_cvt_f32_u32_e32 v0, s14
	s_sub_i32 s16, 0, s14
	s_mulk_i32 s5, 0xb0
	s_sub_i32 s4, s4, s5
	v_rcp_iflag_f32_e32 v0, v0
	s_abs_i32 s5, s4
	s_xor_b32 s15, s4, s13
	s_ashr_i32 s15, s15, 31
	v_mul_f32_e32 v0, 0x4f7ffffe, v0
	v_cvt_u32_f32_e32 v0, v0
	s_mov_b32 s69, 0
	v_readfirstlane_b32 s17, v0
	s_mul_i32 s16, s16, s17
	s_mul_hi_u32 s16, s17, s16
	s_add_i32 s17, s17, s16
	s_mul_hi_u32 s16, s5, s17
	s_mul_i32 s17, s16, s14
	s_sub_i32 s5, s5, s17
	s_add_i32 s17, s16, 1
	s_sub_i32 s18, s5, s14
	s_cmp_ge_u32 s5, s14
	s_cselect_b32 s16, s17, s16
	s_cselect_b32 s5, s18, s5
	s_add_i32 s17, s16, 1
	s_cmp_ge_u32 s5, s14
	s_cselect_b32 s5, s17, s16
	s_xor_b32 s5, s5, s15
	s_sub_i32 s5, s5, s15
	s_mul_i32 s13, s5, s13
	s_sub_i32 s4, s4, s13
	s_add_i32 s5, s5, 2
	s_add_i32 s42, s12, s4
	s_sext_i32_i16 s4, s5
	s_mulk_i32 s4, 0xba3
	s_lshr_b32 s12, s4, 31
	s_lshr_b32 s4, s4, 16
	s_add_i32 s4, s4, s12
	s_mul_i32 s4, s4, 22
	s_sub_i32 s4, s5, s4
	s_sext_i32_i16 s44, s4
